# cumsum phase: serial 512-step prefix loop replaced by 9-step LDS Hillis-Steele scan
# speedup vs baseline: 1.0219x; 1.0076x over previous
.LBB0_759:
	s_or_b64 exec, exec, s[4:5]
	s_mov_b64 s[6:7], s[84:85]
	s_mov_b32 s4, s71
	s_waitcnt lgkmcnt(0)
	s_barrier
	s_cmp_gt_i32 s4, 63
	s_cbranch_scc1 .LBB0_765
	v_mbcnt_lo_u32_b32 v0, -1, 0
	v_mbcnt_hi_u32_b32 v0, -1, v0
	s_getreg_b32 s2, hwreg(HW_REG_HW_ID, 0, 6)
	s_lshl_b32 s2, s2, 2
	s_and_b32 s2, s2, 0xfc
	s_add_i32 s2, s2, 0
	s_add_i32 s2, s2, 0x23400
	v_mov_b32_e32 v2, s2
	ds_read_b32 v2, v2
	s_load_dwordx2 s[6:7], s[6:7], 0x110
	s_ashr_i32 s2, s4, 3
	s_and_b32 s5, s4, 7
	s_waitcnt lgkmcnt(0)
	v_readfirstlane_b32 s3, v2
	s_nop 1
	v_lshl_add_u32 v12, s3, 6, v0
	s_ashr_i32 s3, s2, 31
	v_lshlrev_b32_e32 v2, 3, v12
	s_lshl_b64 s[2:3], s[2:3], 17
	v_ashrrev_i32_e32 v3, 31, v2
	s_add_u32 s2, s6, s2
	s_addc_u32 s3, s7, s3
	v_lshlrev_b64 v[4:5], 5, v[2:3]
	v_lshl_add_u64 v[4:5], s[2:3], 0, v[4:5]
	s_lshl_b32 s50, s5, 2
	v_lshl_add_u64 v[4:5], v[4:5], 0, s[50:51]
	s_mov_b64 s[2:3], 0x500000
	v_lshl_add_u64 v[6:7], v[4:5], 0, s[2:3]
	s_mov_b32 s2, 0x500000
	v_add_co_u32_e32 v4, vcc, s2, v4
	v_mov_b32_e32 v0, 0
	s_nop 0
	v_addc_co_u32_e32 v5, vcc, 0, v5, vcc
	global_load_dword v4, v[4:5], off
	s_nop 0
	global_load_dword v5, v[6:7], off offset:32
	global_load_dword v8, v[6:7], off offset:64
	global_load_dword v9, v[6:7], off offset:96
	global_load_dword v13, v[6:7], off offset:128
	global_load_dword v14, v[6:7], off offset:160
	global_load_dword v15, v[6:7], off offset:192
	global_load_dword v16, v[6:7], off offset:224
	v_lshl_add_u32 v17, v12, 2, 0
	v_cmp_lt_i32_e32 vcc, 0, v12
	s_waitcnt vmcnt(7)
	v_add_f32_e32 v10, 0, v4
	s_waitcnt vmcnt(6)
	v_add_f32_e32 v11, v10, v5
	s_waitcnt vmcnt(5)
	v_add_f32_e32 v8, v11, v8
	s_waitcnt vmcnt(4)
	v_add_f32_e32 v9, v8, v9
	s_waitcnt vmcnt(3)
	v_add_f32_e32 v6, v9, v13
	s_waitcnt vmcnt(2)
	v_add_f32_e32 v7, v6, v14
	s_waitcnt vmcnt(1)
	v_add_f32_e32 v4, v7, v15
	s_waitcnt vmcnt(0)
	v_add_f32_e32 v5, v4, v16
	v_mov_b32_e32 v13, 0
	ds_write_b32 v17, v13
	ds_write_b32 v17, v13 offset:4096
	ds_write_b32 v17, v5 offset:2048
	v_mov_b32_e32 v0, v5
	s_waitcnt lgkmcnt(0)
	s_barrier
	ds_read_b32 v13, v17 offset:2044
	s_waitcnt lgkmcnt(0)
	v_add_f32_e32 v0, v0, v13
	ds_write_b32 v17, v0 offset:6144
	s_waitcnt lgkmcnt(0)
	s_barrier
	ds_read_b32 v13, v17 offset:6136
	s_waitcnt lgkmcnt(0)
	v_add_f32_e32 v0, v0, v13
	ds_write_b32 v17, v0 offset:2048
	s_waitcnt lgkmcnt(0)
	s_barrier
	ds_read_b32 v13, v17 offset:2032
	s_waitcnt lgkmcnt(0)
	v_add_f32_e32 v0, v0, v13
	ds_write_b32 v17, v0 offset:6144
	s_waitcnt lgkmcnt(0)
	s_barrier
	ds_read_b32 v13, v17 offset:6112
	s_waitcnt lgkmcnt(0)
	v_add_f32_e32 v0, v0, v13
	ds_write_b32 v17, v0 offset:2048
	s_waitcnt lgkmcnt(0)
	s_barrier
	ds_read_b32 v13, v17 offset:1984
	s_waitcnt lgkmcnt(0)
	v_add_f32_e32 v0, v0, v13
	ds_write_b32 v17, v0 offset:6144
	s_waitcnt lgkmcnt(0)
	s_barrier
	ds_read_b32 v13, v17 offset:6016
	s_waitcnt lgkmcnt(0)
	v_add_f32_e32 v0, v0, v13
	ds_write_b32 v17, v0 offset:2048
	s_waitcnt lgkmcnt(0)
	s_barrier
	ds_read_b32 v13, v17 offset:1792
	s_waitcnt lgkmcnt(0)
	v_add_f32_e32 v0, v0, v13
	ds_write_b32 v17, v0 offset:6144
	s_waitcnt lgkmcnt(0)
	s_barrier
	ds_read_b32 v13, v17 offset:5632
	s_waitcnt lgkmcnt(0)
	v_add_f32_e32 v0, v0, v13
	ds_write_b32 v17, v0 offset:2048
	s_waitcnt lgkmcnt(0)
	s_barrier
	ds_read_b32 v13, v17 offset:1024
	s_waitcnt lgkmcnt(0)
	v_add_f32_e32 v0, v0, v13
	ds_write_b32 v17, v0 offset:6144
	s_waitcnt lgkmcnt(0)
	s_barrier
	ds_read_b32 v0, v17 offset:6140
	s_waitcnt lgkmcnt(0)
.LBB0_764:
	s_ashr_i32 s5, s4, 31
	s_lshl_b64 s[2:3], s[4:5], 14
	s_add_u32 s2, s6, s2
	s_addc_u32 s3, s7, s3
	v_lshl_add_u64 v[2:3], v[2:3], 2, s[2:3]
	s_mov_b64 s[2:3], 0x600000
	v_lshl_add_u64 v[14:15], v[2:3], 0, s[2:3]
	s_mov_b32 s2, 0x600000
	v_pk_add_f32 v[10:11], v[10:11], v[0:1] op_sel_hi:[1,0]
	s_mov_b32 s4, 0x3fb8aa3b
	v_pk_add_f32 v[8:9], v[8:9], v[0:1] op_sel_hi:[1,0]
	v_add_co_u32_e32 v2, vcc, s2, v2
	v_pk_mul_f32 v[10:11], v[10:11], s[4:5] op_sel_hi:[1,0]
	v_pk_mul_f32 v[12:13], v[8:9], s[4:5] op_sel_hi:[1,0]
	v_addc_co_u32_e32 v3, vcc, 0, v3, vcc
	global_store_dwordx4 v[2:3], v[10:13], off
	v_pk_add_f32 v[2:3], v[6:7], v[0:1] op_sel_hi:[1,0]
	v_pk_add_f32 v[4:5], v[4:5], v[0:1] op_sel_hi:[1,0]
	v_pk_mul_f32 v[2:3], v[2:3], s[4:5] op_sel_hi:[1,0]
	v_pk_mul_f32 v[4:5], v[4:5], s[4:5] op_sel_hi:[1,0]
	global_store_dwordx4 v[14:15], v[2:5], off offset:16
	s_barrier
